# XCD barrier: leader's agent acquire (buffer_inv sc1) issued at arrival (before first poll / before cross-XCD arrival) so its latency overlaps the poll round trips; nothing can refill the CU L1 while a
# speedup vs baseline: 1.0147x; 1.0147x over previous
; DI unsigned xb_ld(unsigned* p)              { return __hip_atomic_load(p, __ATOMIC_RELAXED, __HIP_MEMORY_SCOPE_AGENT); }
; DI unsigned xb_add(unsigned* p, unsigned v) { return __hip_atomic_fetch_add(p, v, __ATOMIC_RELAXED, __HIP_MEMORY_SCOPE_AGENT); }
; #define XB_SPIN(cond, bar) do { unsigned _sp = 0; while (cond) { __builtin_amdgcn_s_sleep(1); \
;     if ((++_sp & 255u) == 0u) { if (xb_ld(&(bar)[XB_TMO])) break; if (_sp > XB_SPIN_CAP) { atomicAdd(&(bar)[XB_TMO], 1u); break; } } } } while (0)
; DI void xcd_barrier(const XcdBarrier& b) {
;     ...
;         unsigned nloc = b.st[0], nx = b.st[1];
;         if (nloc == 0u) { xcd_barrier_complete(bar, b.x, nloc, nx); b.st[0] = nloc; b.st[1] = nx; }
;         const unsigned old = xb_add(&bar[XB_XSUB(b.x)], 1u);
;         const unsigned gen = old / nloc;
;         if (old + 1u == (gen + 1u) * nloc) {
;             __builtin_amdgcn_fence(__ATOMIC_RELEASE, "agent");
;             asm volatile("s_waitcnt vmcnt(0)" ::: "memory");
;             const unsigned og = xb_add(&bar[XB_TOP], 1u);
;             const unsigned tg = og / nx;
;             if (og + 1u == (tg + 1u) * nx) xb_add(&bar[XB_TOPGEN], 1u);
;             else XB_SPIN(xb_ld(&bar[XB_TOPGEN]) == tg, bar);
;             __builtin_amdgcn_fence(__ATOMIC_ACQUIRE, "agent");
;             xb_add(&bar[XB_XGEN(b.x)], 1u);
;             asm volatile("s_waitcnt vmcnt(0)" ::: "memory");
;         } else {
;             XB_SPIN(xb_ld(&bar[XB_XGEN(b.x)]) == gen, bar);
.LBB0_174:
	s_or_b64 exec, exec, s[4:5]
	v_cvt_f32_u32_e32 v6, v3
	s_waitcnt vmcnt(0)
	v_readfirstlane_b32 s0, v5
	v_sub_u32_e32 v5, 0, v3
	v_rcp_iflag_f32_e32 v6, v6
	v_add_u32_e32 v7, s0, v1
	v_mul_f32_e32 v6, 0x4f7ffffe, v6
	v_cvt_u32_f32_e32 v6, v6
	v_mul_lo_u32 v1, v5, v6
	v_mul_hi_u32 v1, v6, v1
	v_add_u32_e32 v1, v6, v1
	v_mul_hi_u32 v1, v7, v1
	v_mul_lo_u32 v5, v1, v3
	v_sub_u32_e32 v5, v7, v5
	v_add_u32_e32 v6, 1, v1
	v_cmp_ge_u32_e32 vcc, v5, v3
	s_nop 1
	v_cndmask_b32_e32 v1, v1, v6, vcc
	v_sub_u32_e32 v6, v5, v3
	v_cndmask_b32_e32 v5, v5, v6, vcc
	v_add_u32_e32 v6, 1, v1
	v_cmp_ge_u32_e32 vcc, v5, v3
	v_add_u32_e32 v5, 1, v7
	s_nop 0
	v_cndmask_b32_e32 v1, v1, v6, vcc
	v_mul_lo_u32 v6, v3, v1
	v_add_u32_e32 v3, v6, v3
	v_cmp_ne_u32_e32 vcc, v5, v3
	s_and_saveexec_b64 s[0:1], vcc
	s_xor_b64 s[4:5], exec, s[0:1]
	s_cbranch_execz .LBB0_188
	v_readlane_b32 s0, v253, 47
	v_readlane_b32 s1, v253, 48
	s_waitcnt lgkmcnt(0)
	s_nop 3
	buffer_inv sc1
	global_load_dword v2, v0, s[0:1] sc1
	s_waitcnt vmcnt(0)
	v_cmp_eq_u32_e32 vcc, v2, v1
	s_and_saveexec_b64 s[6:7], vcc
	s_cbranch_execz .LBB0_187
	s_mov_b32 s0, 1
	s_mov_b64 s[8:9], 0
	s_branch .LBB0_178

; DI unsigned xb_ld(unsigned* p)              { return __hip_atomic_load(p, __ATOMIC_RELAXED, __HIP_MEMORY_SCOPE_AGENT); }
; DI unsigned xb_add(unsigned* p, unsigned v) { return __hip_atomic_fetch_add(p, v, __ATOMIC_RELAXED, __HIP_MEMORY_SCOPE_AGENT); }
; #define XB_SPIN(cond, bar) do { unsigned _sp = 0; while (cond) { __builtin_amdgcn_s_sleep(1); \
;     if ((++_sp & 255u) == 0u) { if (xb_ld(&(bar)[XB_TMO])) break; if (_sp > XB_SPIN_CAP) { atomicAdd(&(bar)[XB_TMO], 1u); break; } } } } while (0)
; DI void xcd_barrier(const XcdBarrier& b) {
;     ...
;         if (old + 1u == (gen + 1u) * nloc) {
;             __builtin_amdgcn_fence(__ATOMIC_RELEASE, "agent");
;             asm volatile("s_waitcnt vmcnt(0)" ::: "memory");
;             const unsigned og = xb_add(&bar[XB_TOP], 1u);
;             const unsigned tg = og / nx;
;             if (og + 1u == (tg + 1u) * nx) xb_add(&bar[XB_TOPGEN], 1u);
;             else XB_SPIN(xb_ld(&bar[XB_TOPGEN]) == tg, bar);
;             __builtin_amdgcn_fence(__ATOMIC_ACQUIRE, "agent");
.LBB0_187:
	s_or_b64 exec, exec, s[6:7]
	s_waitcnt vmcnt(0)
	s_waitcnt vmcnt(0)
.LBB0_188:
	s_andn2_saveexec_b64 s[4:5], s[4:5]
	s_cbranch_execz .LBB0_208
	s_mov_b64 s[6:7], exec
	buffer_wbl2 sc1
	s_waitcnt lgkmcnt(0)
	s_waitcnt vmcnt(0)
	v_mbcnt_lo_u32_b32 v1, s6, 0
	v_mbcnt_hi_u32_b32 v1, s7, v1
	v_cmp_eq_u32_e32 vcc, 0, v1
	s_and_saveexec_b64 s[8:9], vcc
	s_cbranch_execz .LBB0_191
	s_bcnt1_i32_b64 s0, s[6:7]
	v_mov_b32_e32 v3, s0
	v_readlane_b32 s0, v253, 45
	v_readlane_b32 s1, v253, 46
	s_nop 4
	buffer_inv sc1
	global_atomic_add v3, v0, v3, s[0:1] sc0

; DI unsigned xb_ld(unsigned* p)              { return __hip_atomic_load(p, __ATOMIC_RELAXED, __HIP_MEMORY_SCOPE_AGENT); }
; DI unsigned xb_add(unsigned* p, unsigned v) { return __hip_atomic_fetch_add(p, v, __ATOMIC_RELAXED, __HIP_MEMORY_SCOPE_AGENT); }
; #define XB_SPIN(cond, bar) do { unsigned _sp = 0; while (cond) { __builtin_amdgcn_s_sleep(1); \
;     if ((++_sp & 255u) == 0u) { if (xb_ld(&(bar)[XB_TMO])) break; if (_sp > XB_SPIN_CAP) { atomicAdd(&(bar)[XB_TMO], 1u); break; } } } } while (0)
; DI void xcd_barrier(const XcdBarrier& b) {
;     ...
;             else XB_SPIN(xb_ld(&bar[XB_TOPGEN]) == tg, bar);
;             __builtin_amdgcn_fence(__ATOMIC_ACQUIRE, "agent");
;             xb_add(&bar[XB_XGEN(b.x)], 1u);
.LBB0_205:
	s_or_b64 exec, exec, s[6:7]
	s_mov_b64 s[6:7], exec
	v_mbcnt_lo_u32_b32 v1, s6, 0
	v_mbcnt_hi_u32_b32 v1, s7, v1
	v_cmp_eq_u32_e32 vcc, 0, v1
	s_waitcnt vmcnt(0)
	s_and_saveexec_b64 s[8:9], vcc
	s_cbranch_execz .LBB0_207
	s_bcnt1_i32_b64 s0, s[6:7]
	v_mov_b32_e32 v1, s0
	v_readlane_b32 s0, v253, 43
	v_readlane_b32 s1, v253, 44
	s_nop 4

; DI unsigned xb_add(unsigned* p, unsigned v) { return __hip_atomic_fetch_add(p, v, __ATOMIC_RELAXED, __HIP_MEMORY_SCOPE_AGENT); }
; DI void xcd_barrier(const XcdBarrier& b) {
;     ...
;         if (old + 1u == (gen + 1u) * nloc) {
;             __builtin_amdgcn_fence(__ATOMIC_RELEASE, "agent");
;             asm volatile("s_waitcnt vmcnt(0)" ::: "memory");
;             const unsigned og = xb_add(&bar[XB_TOP], 1u);
.LBB0_373:
	s_andn2_saveexec_b64 s[0:1], s[4:5]
	s_cbranch_execz .LBB0_393
	s_mov_b64 s[4:5], exec
	buffer_wbl2 sc1
	s_waitcnt lgkmcnt(0)
	s_waitcnt vmcnt(0)
	v_mbcnt_lo_u32_b32 v1, s4, 0
	v_mbcnt_hi_u32_b32 v1, s5, v1
	v_cmp_eq_u32_e32 vcc, 0, v1
	s_and_saveexec_b64 s[6:7], vcc
	s_cbranch_execz .LBB0_376
	s_bcnt1_i32_b64 s0, s[4:5]
	v_mov_b32_e32 v3, s0
	v_readlane_b32 s0, v253, 45
	v_readlane_b32 s1, v253, 46
	s_nop 4
	buffer_inv sc1
	global_atomic_add v3, v0, v3, s[0:1] sc0

; DI unsigned xb_ld(unsigned* p)              { return __hip_atomic_load(p, __ATOMIC_RELAXED, __HIP_MEMORY_SCOPE_AGENT); }
; DI unsigned xb_add(unsigned* p, unsigned v) { return __hip_atomic_fetch_add(p, v, __ATOMIC_RELAXED, __HIP_MEMORY_SCOPE_AGENT); }
; #define XB_SPIN(cond, bar) do { unsigned _sp = 0; while (cond) { __builtin_amdgcn_s_sleep(1); \
;     if ((++_sp & 255u) == 0u) { if (xb_ld(&(bar)[XB_TMO])) break; if (_sp > XB_SPIN_CAP) { atomicAdd(&(bar)[XB_TMO], 1u); break; } } } } while (0)
; DI void xcd_barrier(const XcdBarrier& b) {
;     ...
;             else XB_SPIN(xb_ld(&bar[XB_TOPGEN]) == tg, bar);
;             __builtin_amdgcn_fence(__ATOMIC_ACQUIRE, "agent");
;             xb_add(&bar[XB_XGEN(b.x)], 1u);
.LBB0_390:
	s_or_b64 exec, exec, s[4:5]
	s_mov_b64 s[4:5], exec
	v_mbcnt_lo_u32_b32 v1, s4, 0
	v_mbcnt_hi_u32_b32 v1, s5, v1
	v_cmp_eq_u32_e32 vcc, 0, v1
	s_waitcnt vmcnt(0)
	s_and_saveexec_b64 s[6:7], vcc
	s_cbranch_execz .LBB0_392
	s_bcnt1_i32_b64 s0, s[4:5]
	v_mov_b32_e32 v1, s0
	v_readlane_b32 s0, v253, 43
	v_readlane_b32 s1, v253, 44
	s_nop 4

; DI unsigned xb_ld(unsigned* p)              { return __hip_atomic_load(p, __ATOMIC_RELAXED, __HIP_MEMORY_SCOPE_AGENT); }
; DI unsigned xb_add(unsigned* p, unsigned v) { return __hip_atomic_fetch_add(p, v, __ATOMIC_RELAXED, __HIP_MEMORY_SCOPE_AGENT); }
; #define XB_SPIN(cond, bar) do { unsigned _sp = 0; while (cond) { __builtin_amdgcn_s_sleep(1); \
;     if ((++_sp & 255u) == 0u) { if (xb_ld(&(bar)[XB_TMO])) break; if (_sp > XB_SPIN_CAP) { atomicAdd(&(bar)[XB_TMO], 1u); break; } } } } while (0)
; DI void xcd_barrier(const XcdBarrier& b) {
;     ...
;             else XB_SPIN(xb_ld(&bar[XB_TOPGEN]) == tg, bar);
;             __builtin_amdgcn_fence(__ATOMIC_ACQUIRE, "agent");
;             xb_add(&bar[XB_XGEN(b.x)], 1u);
.LBB0_874:
	s_or_b64 exec, exec, s[4:5]
	s_mov_b64 s[4:5], exec
	v_mbcnt_lo_u32_b32 v1, s4, 0
	v_mbcnt_hi_u32_b32 v1, s5, v1
	v_cmp_eq_u32_e32 vcc, 0, v1
	s_waitcnt vmcnt(0)
	s_and_saveexec_b64 s[6:7], vcc
	s_cbranch_execz .LBB0_72
	s_bcnt1_i32_b64 s0, s[4:5]
	v_mov_b32_e32 v1, s0
	v_readlane_b32 s0, v253, 43
	v_readlane_b32 s1, v253, 44
	s_nop 4
	s_branch .LBB0_72
